# w22: w9 + non-temporal (nt) policy on the XBLK conversion stream stores in FFN1-in phase (written once, read three phases later)
# speedup vs baseline: 1.0128x; 1.0048x over previous
; DI unsigned pk2(float lo, float hi) { f32x2 v = {lo, hi}; bf16x2_t b = __builtin_convertvector(v, bf16x2_t); return __builtin_bit_cast(unsigned, b); }
; DI void xblk_part(Frame& F, int rank, int nranks) {
;     ...
;     for (int it0 = gw * 4; it0 < NDB * 2048; it0 += NGW * 4) {
;         f32x4 v[4][2];
; #pragma unroll
;         for (int q = 0; q < 4; ++q) { const int it = it0 + q, s = it >> 11, row = it & 2047; const int page = F.ptab[s * 16 + (row >> 7)];
;             const float* src = F.c_cmp + ((size_t)page * 128 + (row & 127)) * 512;
;             v[q][0] = __builtin_nontemporal_load((const f32x4*)(src + 4 * lane)); v[q][1] = __builtin_nontemporal_load((const f32x4*)(src + 4 * (lane + 64))); }
; #pragma unroll
;         for (int q = 0; q < 4; ++q) { const int it = it0 + q, s = it >> 11, row = it & 2047;
; #pragma unroll
;             for (int j = 0; j < 2; ++j) { const int e = lane + 64 * j, kvsel = e >> 6, h = (e >> 4) & 3, d4 = (e & 15) * 4;
;                 u32x2 w; w.x = pk2(v[q][j][0], v[q][j][1]); w.y = pk2(v[q][j][2], v[q][j][3]);
;                 *(u32x2*)(F.XBLK + ((size_t)kvsel * XROWS + (size_t)(s * 4 + h) * 128 + (row >> 4)) * 1024 + (row & 15) * 64 + d4) = w; } }
;     }
.LBB0_89:
	s_ashr_i32 s0, s12, 7
	s_bfe_u32 s20, s12, 0x40007
	s_and_b32 s0, s0, -16
	s_or_b32 s20, s0, s20
	s_ashr_i32 s21, s20, 31
	s_lshl_b64 s[20:21], s[20:21], 2
	s_add_u32 s20, s48, s20
	s_addc_u32 s21, s49, s21
	global_load_dword v7, v3, s[20:21]
	s_waitcnt vmcnt(0)
	v_readfirstlane_b32 s20, v7
	s_ashr_i32 s21, s20, 31
	s_lshl_b64 s[20:21], s[20:21], 18
	s_add_u32 s0, s40, s20
	s_addc_u32 s21, s41, s21
	s_and_b32 s20, s18, 0xf800
	s_lshl_b32 s20, s20, 2
	s_add_u32 s20, s0, s20
	s_addc_u32 s21, s21, 0
	s_add_u32 s22, s20, 0x1000
	s_addc_u32 s23, s21, 0
	s_waitcnt lgkmcnt(0)
	global_load_dwordx4 v[8:11], v5, s[20:21] nt
	global_load_dwordx4 v[12:15], v5, s[20:21] offset:1024 nt
	global_load_dwordx4 v[16:19], v5, s[20:21] offset:2048 nt
	global_load_dwordx4 v[20:23], v5, s[20:21] offset:3072 nt
	s_add_u32 s20, s20, 0x1800
	global_load_dwordx4 v[24:27], v5, s[22:23] nt
	global_load_dwordx4 v[28:31], v6, s[22:23] nt
	s_addc_u32 s21, s21, 0
	global_load_dwordx4 v[32:35], v5, s[20:21] nt
	global_load_dwordx4 v[36:39], v6, s[20:21] nt
	s_ashr_i32 s20, s12, 9
	v_and_or_b32 v40, s20, -4, v4
	v_ashrrev_i32_e32 v41, 31, v40
	v_lshlrev_b64 v[40:41], 18, v[40:41]
	s_and_b32 s0, s14, 0x3f800
	s_lshl_b32 s22, s16, 1
	v_lshl_add_u64 v[40:41], s[62:63], 0, v[40:41]
	v_lshl_add_u64 v[40:41], v[40:41], 0, s[0:1]
	s_and_b32 s0, s22, 0x600
	v_lshl_add_u64 v[42:43], v[40:41], 0, s[0:1]
	v_lshl_add_u64 v[40:41], v[40:41], 0, s[10:11]
	s_mov_b32 s21, s1
	s_or_b32 s20, s0, 0x80
	v_lshl_add_u64 v[42:43], v[42:43], 0, v[2:3]
	v_lshl_add_u64 v[44:45], v[40:41], 0, s[0:1]
	v_lshl_add_u64 v[40:41], v[40:41], 0, v[2:3]
	s_mov_b32 s23, s1
	s_add_i32 s12, s12, s13
	s_add_i32 s14, s14, s15
	s_add_i32 s16, s16, s17
	s_add_i32 s18, s18, s19
	s_or_b32 s22, s0, 0x100
	s_or_b32 s0, s0, 0x180
	v_lshl_add_u64 v[44:45], v[44:45], 0, v[2:3]
	v_lshl_add_u64 v[46:47], v[40:41], 0, s[20:21]
	v_lshl_add_u64 v[48:49], v[40:41], 0, s[22:23]
	s_cmp_lt_i32 s12, 0x40000
	v_lshl_add_u64 v[40:41], v[40:41], 0, s[0:1]
	s_waitcnt vmcnt(7)
	v_cvt_pk_bf16_f32 v8, v8, v9
	v_cvt_pk_bf16_f32 v9, v10, v11
	s_waitcnt vmcnt(6)
	v_cvt_pk_bf16_f32 v10, v12, v13
	v_cvt_pk_bf16_f32 v11, v14, v15
	s_waitcnt vmcnt(5)
	v_cvt_pk_bf16_f32 v12, v16, v17
	v_cvt_pk_bf16_f32 v13, v18, v19
	s_waitcnt vmcnt(4)
	v_cvt_pk_bf16_f32 v14, v20, v21
	v_cvt_pk_bf16_f32 v15, v22, v23
	global_store_dwordx2 v[42:43], v[8:9], off nt
	global_store_dwordx2 v[44:45], v[10:11], off nt
	global_store_dwordx2 v[42:43], v[12:13], off offset:128 nt
	global_store_dwordx2 v[46:47], v[14:15], off nt
	s_waitcnt vmcnt(7)
	v_cvt_pk_bf16_f32 v8, v24, v25
	v_cvt_pk_bf16_f32 v9, v26, v27
	s_waitcnt vmcnt(6)
	v_cvt_pk_bf16_f32 v10, v28, v29
	v_cvt_pk_bf16_f32 v11, v30, v31
	global_store_dwordx2 v[42:43], v[8:9], off offset:256 nt
	global_store_dwordx2 v[48:49], v[10:11], off nt
	s_waitcnt vmcnt(7)
	v_cvt_pk_bf16_f32 v8, v32, v33
	v_cvt_pk_bf16_f32 v9, v34, v35
	s_waitcnt vmcnt(6)
	v_cvt_pk_bf16_f32 v10, v36, v37
	v_cvt_pk_bf16_f32 v11, v38, v39
	global_store_dwordx2 v[42:43], v[8:9], off offset:384 nt
	global_store_dwordx2 v[40:41], v[10:11], off nt
	s_cbranch_scc1 .LBB0_89

; DI unsigned pk2(float lo, float hi) { f32x2 v = {lo, hi}; bf16x2_t b = __builtin_convertvector(v, bf16x2_t); return __builtin_bit_cast(unsigned, b); }
; DI void xblk_part(Frame& F, int rank, int nranks) {
;     ...
;     for (int it0 = gw * 4; it0 < NDB * 2048; it0 += NGW * 4) {
;         f32x4 v[4][2];
; #pragma unroll
;         for (int q = 0; q < 4; ++q) { const int it = it0 + q, s = it >> 11, row = it & 2047; const int page = F.ptab[s * 16 + (row >> 7)];
;             const float* src = F.c_cmp + ((size_t)page * 128 + (row & 127)) * 512;
;             v[q][0] = __builtin_nontemporal_load((const f32x4*)(src + 4 * lane)); v[q][1] = __builtin_nontemporal_load((const f32x4*)(src + 4 * (lane + 64))); }
; #pragma unroll
;         for (int q = 0; q < 4; ++q) { const int it = it0 + q, s = it >> 11, row = it & 2047;
; #pragma unroll
;             for (int j = 0; j < 2; ++j) { const int e = lane + 64 * j, kvsel = e >> 6, h = (e >> 4) & 3, d4 = (e & 15) * 4;
;                 u32x2 w; w.x = pk2(v[q][j][0], v[q][j][1]); w.y = pk2(v[q][j][2], v[q][j][3]);
;                 *(u32x2*)(F.XBLK + ((size_t)kvsel * XROWS + (size_t)(s * 4 + h) * 128 + (row >> 4)) * 1024 + (row & 15) * 64 + d4) = w; } }
;     }
.LBB0_110:
	s_ashr_i32 s0, s8, 7
	s_bfe_u32 s16, s8, 0x40007
	s_and_b32 s0, s0, -16
	s_or_b32 s16, s0, s16
	s_ashr_i32 s17, s16, 31
	s_lshl_b64 s[16:17], s[16:17], 2
	s_add_u32 s16, s48, s16
	s_addc_u32 s17, s49, s17
	global_load_dword v7, v3, s[16:17]
	s_waitcnt vmcnt(0)
	v_readfirstlane_b32 s16, v7
	s_ashr_i32 s17, s16, 31
	s_lshl_b64 s[16:17], s[16:17], 18
	s_add_u32 s0, s40, s16
	s_addc_u32 s17, s41, s17
	s_and_b32 s16, s14, 0xf800
	s_lshl_b32 s16, s16, 2
	s_add_u32 s16, s0, s16
	s_addc_u32 s17, s17, 0
	s_add_u32 s18, s16, 0x1000
	s_addc_u32 s19, s17, 0
	global_load_dwordx4 v[8:11], v5, s[16:17] nt
	global_load_dwordx4 v[12:15], v5, s[16:17] offset:1024 nt
	global_load_dwordx4 v[16:19], v5, s[16:17] offset:2048 nt
	global_load_dwordx4 v[20:23], v5, s[16:17] offset:3072 nt
	s_add_u32 s16, s16, 0x1800
	global_load_dwordx4 v[24:27], v5, s[18:19] nt
	global_load_dwordx4 v[28:31], v6, s[18:19] nt
	s_addc_u32 s17, s17, 0
	global_load_dwordx4 v[32:35], v5, s[16:17] nt
	global_load_dwordx4 v[36:39], v6, s[16:17] nt
	s_ashr_i32 s16, s8, 9
	v_and_or_b32 v40, s16, -4, v4
	v_ashrrev_i32_e32 v41, 31, v40
	v_lshlrev_b64 v[40:41], 18, v[40:41]
	s_and_b32 s0, s10, 0x3f800
	s_lshl_b32 s18, s12, 1
	v_lshl_add_u64 v[40:41], s[62:63], 0, v[40:41]
	v_lshl_add_u64 v[40:41], v[40:41], 0, s[0:1]
	s_and_b32 s0, s18, 0x600
	v_lshl_add_u64 v[42:43], v[40:41], 0, s[0:1]
	v_lshl_add_u64 v[40:41], v[40:41], 0, s[6:7]
	s_mov_b32 s17, s1
	s_or_b32 s16, s0, 0x80
	v_lshl_add_u64 v[42:43], v[42:43], 0, v[2:3]
	v_lshl_add_u64 v[44:45], v[40:41], 0, s[0:1]
	v_lshl_add_u64 v[40:41], v[40:41], 0, v[2:3]
	s_mov_b32 s19, s1
	s_add_i32 s8, s8, s9
	s_add_i32 s10, s10, s11
	s_add_i32 s12, s12, s13
	s_add_i32 s14, s14, s15
	s_or_b32 s18, s0, 0x100
	s_or_b32 s0, s0, 0x180
	v_lshl_add_u64 v[44:45], v[44:45], 0, v[2:3]
	v_lshl_add_u64 v[46:47], v[40:41], 0, s[16:17]
	v_lshl_add_u64 v[48:49], v[40:41], 0, s[18:19]
	s_cmp_lt_i32 s8, 0x40000
	v_lshl_add_u64 v[40:41], v[40:41], 0, s[0:1]
	s_waitcnt vmcnt(7)
	v_cvt_pk_bf16_f32 v8, v8, v9
	v_cvt_pk_bf16_f32 v9, v10, v11
	s_waitcnt vmcnt(6)
	v_cvt_pk_bf16_f32 v10, v12, v13
	v_cvt_pk_bf16_f32 v11, v14, v15
	s_waitcnt vmcnt(5)
	v_cvt_pk_bf16_f32 v12, v16, v17
	v_cvt_pk_bf16_f32 v13, v18, v19
	s_waitcnt vmcnt(4)
	v_cvt_pk_bf16_f32 v14, v20, v21
	v_cvt_pk_bf16_f32 v15, v22, v23
	global_store_dwordx2 v[42:43], v[8:9], off nt
	global_store_dwordx2 v[44:45], v[10:11], off nt
	global_store_dwordx2 v[42:43], v[12:13], off offset:128 nt
	global_store_dwordx2 v[46:47], v[14:15], off nt
	s_waitcnt vmcnt(7)
	v_cvt_pk_bf16_f32 v8, v24, v25
	v_cvt_pk_bf16_f32 v9, v26, v27
	s_waitcnt vmcnt(6)
	v_cvt_pk_bf16_f32 v10, v28, v29
	v_cvt_pk_bf16_f32 v11, v30, v31
	global_store_dwordx2 v[42:43], v[8:9], off offset:256 nt
	global_store_dwordx2 v[48:49], v[10:11], off nt
	s_waitcnt vmcnt(7)
	v_cvt_pk_bf16_f32 v8, v32, v33
	v_cvt_pk_bf16_f32 v9, v34, v35
	s_waitcnt vmcnt(6)
	v_cvt_pk_bf16_f32 v10, v36, v37
	v_cvt_pk_bf16_f32 v11, v38, v39
	global_store_dwordx2 v[42:43], v[8:9], off offset:384 nt
	global_store_dwordx2 v[40:41], v[10:11], off nt
	s_cbranch_scc1 .LBB0_110
